# attention: next unit's gain/sink/Q loads issued before this unit's output stores (counted waits skip the store drain)
# baseline (speedup 1.0000x reference)
; #define LAS __attribute__((address_space(3)))
; #define AT_SYNC() do { asm volatile("s_waitcnt vmcnt(0) lgkmcnt(0)" ::: "memory"); __builtin_amdgcn_s_barrier(); asm volatile("" ::: "memory"); } while (0)
; __device__ __forceinline__ bool attn_unit(const Ptrs& P, LAS unsigned char* lds, int unit, int tid, int wave, int lane, bool pre, int nxt) {
;     const int n = unit & 31, kh = (unit >> 5) & 3, b = unit >> 7;
;     const int g = wave & 3, q0 = 64 * (wave >> 2), h = kh * 4 + g, r = lane & 31, hh = lane >> 5;
;     unsigned char* ws = P.ws;
;     bf16_t* Qb = (bf16_t*)(ws + WS_Q) + (size_t)(b * SEQ + n * 128 + q0) * DM + h * 64;
;     const bf16_t* Kg = (const bf16_t*)(ws + WS_K) + (size_t)b * SEQ * KVW + kh * 64; const bf16_t* Vg = (const bf16_t*)(ws + WS_VT) + (size_t)(b * 4 + kh) * 64 * SEQ;
;     const bf16_t* Kcg = (const bf16_t*)(ws + WS_KC) + (size_t)b * CTX * KVW + kh * 64; const bf16_t* Vcg = (const bf16_t*)(ws + WS_VCT) + (size_t)(b * 4 + kh) * 64 * CTX;
;     float mq = fabsf(P.qg[lane]), mk = fabsf(P.kg[lane]);
; #pragma unroll
;     for (int o = 1; o < 64; o <<= 1) { mq = fmaxf(mq, __shfl_xor(mq, o)); mk = fmaxf(mk, __shfl_xor(mk, o)); }
;     const float sink2 = P.sink[h] * LOG2E; const float mshift = fmaxf(64.0f * QSCALE * mq * mk, sink2);
;     bf16x8_t qf[2][4];
; #pragma unroll
;     for (int cb = 0; cb < 2; ++cb)
; #pragma unroll
;         for (int ds = 0; ds < 4; ++ds) qf[cb][ds] = __builtin_nontemporal_load((const bf16x8_t*)(Qb + (size_t)(32 * cb + r) * DM + 16 * ds + 8 * hh));
;     f32x16 o[2][2];
; #pragma unroll
;     for (int db = 0; db < 2; ++db)
; #pragma unroll
;         for (int cb = 0; cb < 2; ++cb)
; #pragma unroll
;             for (int i = 0; i < 16; ++i) o[db][cb][i] = 0.f;
;     float rs[2] = {0.f, 0.f};
;     f32x16 negm;
; #pragma unroll
;     for (int i = 0; i < 16; ++i) negm[i] = -mshift;
;     ...
;     if (!pre) { if (n == 0) AT_DMA(1); else AT_DMA(0); }
;     AT_SYNC();
;     const int n2 = nxt & 31; const bool pf = nxt >= 0 && n2 != 0;
.LBB9_305:
	s_cmp_lt_i32 s92, 4
	s_cselect_b64 s[2:3], -1, 0
	s_and_b64 s[22:23], s[2:3], s[0:1]
	s_andn2_b64 vcc, exec, s[22:23]
	s_cbranch_vccnz .LBB9_444
	v_writelane_b32 v251, s22, 33
	s_cmpk_gt_i32 s97, 0x1ff
	v_and_b32_e32 v171, 31, v208
	v_writelane_b32 v251, s23, 34
	v_writelane_b32 v251, s80, 35
	v_lshrrev_b32_e32 v184, 5, v170
	s_nop 0
	v_writelane_b32 v251, s81, 36
	v_writelane_b32 v251, s96, 37
	v_writelane_b32 v251, s83, 38
	v_writelane_b32 v251, s97, 39
	s_cbranch_scc1 .LBB9_413
	v_mbcnt_lo_u32_b32 v0, -1, 0
	v_mbcnt_hi_u32_b32 v0, -1, v0
	v_and_b32_e32 v1, 64, v0
	v_add_u32_e32 v1, 64, v1
	v_xor_b32_e32 v2, 1, v0
	v_cmp_lt_i32_e32 vcc, v2, v1
	s_bfe_u32 s0, s40, 0x20006
	v_writelane_b32 v251, s0, 40
	v_cndmask_b32_e32 v2, v0, v2, vcc
	v_lshlrev_b32_e32 v185, 2, v2
	v_xor_b32_e32 v2, 2, v0
	v_cmp_lt_i32_e32 vcc, v2, v1
	s_lshl_b32 s0, s50, 4
	s_and_b32 s33, s0, 0x3fffffc0
	v_cndmask_b32_e32 v2, v0, v2, vcc
	v_lshlrev_b32_e32 v186, 2, v2
	v_xor_b32_e32 v2, 4, v0
	v_cmp_lt_i32_e32 vcc, v2, v1
	s_cmpk_lt_u32 s40, 0x8c0
	s_cselect_b64 s[54:55], -1, 0
	v_cndmask_b32_e32 v2, v0, v2, vcc
	v_lshlrev_b32_e32 v187, 2, v2
	v_xor_b32_e32 v2, 8, v0
	v_cmp_lt_i32_e32 vcc, v2, v1
	s_or_b32 s2, s0, 63
	s_or_b32 s3, s33, 32
	v_cndmask_b32_e32 v2, v0, v2, vcc
	v_lshlrev_b32_e32 v188, 2, v2
	v_xor_b32_e32 v2, 16, v0
	v_cmp_lt_i32_e32 vcc, v2, v1
	v_or_b32_e32 v5, 32, v170
	v_lshlrev_b32_e32 v191, 4, v184
	v_cndmask_b32_e32 v2, v0, v2, vcc
	v_lshlrev_b32_e32 v189, 2, v2
	v_xor_b32_e32 v2, 32, v0
	v_cmp_lt_i32_e32 vcc, v2, v1
	v_mov_b32_e32 v1, 0
	v_mul_u32_u24_e32 v6, 0x110, v5
	v_cndmask_b32_e32 v0, v0, v2, vcc
	v_lshlrev_b32_e32 v190, 2, v0
	v_lshlrev_b32_e32 v0, 2, v184
	v_sub_u32_e32 v0, v171, v0
	v_cmp_lt_i32_e64 s[36:37], 10, v0
	v_cmp_gt_i32_e64 s[0:1], 1, v0
	v_cmp_gt_i32_e64 s[4:5], 2, v0
	v_writelane_b32 v251, s36, 41
	v_cmp_gt_i32_e64 s[6:7], 3, v0
	v_cmp_gt_i32_e64 s[8:9], 4, v0
	v_writelane_b32 v251, s37, 42
	v_cmp_lt_i32_e64 s[36:37], 15, v0
	v_cmp_gt_i32_e64 s[10:11], 9, v0
	v_cmp_gt_i32_e64 s[12:13], 10, v0
	v_writelane_b32 v251, s36, 43
	v_cmp_gt_i32_e64 s[14:15], 11, v0
	v_cmp_gt_i32_e64 s[16:17], 12, v0
	v_writelane_b32 v251, s37, 44
	v_cmp_lt_i32_e64 s[36:37], 16, v0
	v_cmp_gt_i32_e64 s[18:19], 17, v0
	v_cmp_gt_i32_e64 s[20:21], 18, v0
	v_writelane_b32 v251, s36, 45
	v_cmp_gt_i32_e64 s[22:23], 19, v0
	v_cmp_gt_i32_e64 s[24:25], 20, v0
	v_writelane_b32 v251, s37, 46
	v_cmp_lt_i32_e64 s[36:37], 17, v0
	v_cmp_gt_i32_e64 s[26:27], 25, v0
	v_cmp_gt_i32_e64 s[28:29], 26, v0
	v_writelane_b32 v251, s36, 47
	v_cmp_gt_i32_e64 s[30:31], 27, v0
	v_cmp_gt_i32_e64 s[34:35], 28, v0
	v_writelane_b32 v251, s37, 48
	v_cmp_lt_i32_e64 s[36:37], 18, v0
	v_cmp_lt_i32_e64 s[56:57], -1, v0
	v_cmp_lt_i32_e64 s[86:87], 0, v0
	v_writelane_b32 v251, s36, 49
	v_cmp_lt_i32_e64 s[60:61], 1, v0
	v_cmp_lt_i32_e64 s[62:63], 2, v0
	v_writelane_b32 v251, s37, 50
	v_cmp_lt_i32_e64 s[36:37], 23, v0
	v_cmp_lt_i32_e64 s[64:65], 7, v0
	v_cmp_lt_i32_e64 s[66:67], 8, v0
	v_writelane_b32 v251, s36, 51
	v_cmp_lt_i32_e64 s[72:73], 9, v0
	v_lshlrev_b32_e32 v4, 3, v184
	v_writelane_b32 v251, s37, 52
	v_cmp_lt_i32_e64 s[36:37], 24, v0
	v_mul_u32_u24_e32 v3, 0x110, v171
	v_lshlrev_b32_e32 v2, 10, v171
	v_writelane_b32 v251, s36, 53
	s_movk_i32 s52, 0x110
	v_add3_u32 v3, v3, v191, 0
	v_writelane_b32 v251, s37, 54
	v_cmp_lt_i32_e64 s[36:37], 25, v0
	v_lshlrev_b32_e32 v176, 1, v4
	s_mov_b32 s77, 0
	v_writelane_b32 v251, s36, 55
	v_add_u32_e32 v195, 0x4800, v3
	v_add_u32_e32 v198, 0xd400, v3
	v_writelane_b32 v251, s37, 56
	v_cmp_lt_i32_e64 s[36:37], 26, v0
	v_lshlrev_b32_e32 v0, 2, v170
	v_mad_u32_u24 v200, v5, s52, 0
	v_writelane_b32 v251, s36, 57
	v_mad_u32_u24 v201, v171, s52, 0
	s_mov_b64 s[68:69], 0
	v_writelane_b32 v251, s37, 58
	s_add_u32 s36, s90, 0x6200000
	v_writelane_b32 v251, s36, 59
	s_addc_u32 s36, s91, 0
	v_writelane_b32 v251, s36, 60
	s_add_u32 s36, s90, 0x7200000
	v_writelane_b32 v251, s36, 61
	s_addc_u32 s36, s91, 0
	v_writelane_b32 v251, s36, 62
	v_mov_b32_e32 v178, v176
	v_readlane_b32 s36, v251, 16
	s_add_u32 s36, s90, 0x4200000
	v_readlane_b32 s37, v251, 17
	v_readlane_b32 s38, v251, 18
	v_readlane_b32 s39, v251, 19
	v_readlane_b32 s40, v251, 20
	v_readlane_b32 s41, v251, 21
	v_readlane_b32 s42, v251, 22
	v_readlane_b32 s43, v251, 23
	v_readlane_b32 s44, v251, 24
	v_readlane_b32 s45, v251, 25
	v_readlane_b32 s46, v251, 26
	v_readlane_b32 s47, v251, 27
	v_readlane_b32 s48, v251, 28
	v_readlane_b32 s49, v251, 29
	v_readlane_b32 s50, v251, 30
	v_readlane_b32 s51, v251, 31
	v_writelane_b32 v251, s36, 63
	s_addc_u32 s36, s91, 0
	v_writelane_b32 v250, s36, 0
	s_add_u32 s36, s90, 0x6a00000
	v_writelane_b32 v250, s36, 1
	s_addc_u32 s36, s91, 0
	v_writelane_b32 v250, s36, 2
	s_add_u32 s36, s90, 0x7280000
	v_writelane_b32 v250, s36, 3
	s_addc_u32 s36, s91, 0
	v_writelane_b32 v250, s36, 4
	s_add_u32 s36, s90, 0x2000000
	v_writelane_b32 v250, s36, 5
	s_addc_u32 s36, s91, 0
	v_lshl_add_u64 v[172:173], s[40:41], 0, v[0:1]
	v_writelane_b32 v250, s36, 6
	s_add_i32 s40, 0, 0x11800
	s_add_i32 s76, 0, 0x16000
	v_writelane_b32 v250, s40, 7
	v_writelane_b32 v250, s76, 8
	v_writelane_b32 v250, s88, 9
	v_lshl_add_u64 v[174:175], s[42:43], 0, v[0:1]
	v_readlane_b32 s36, v251, 32
	v_writelane_b32 v250, s89, 10
	v_writelane_b32 v250, s90, 11
	v_writelane_b32 v250, s91, 12
	v_add3_u32 v0, v6, v191, 0
	v_mul_u32_u24_e32 v6, 0x90, v171
	v_writelane_b32 v250, s92, 13
	v_lshl_or_b32 v192, s36, 6, v170
	s_movk_i32 s37, 0x90
	v_add3_u32 v196, v6, v191, 0
	v_writelane_b32 v250, s93, 14
	v_add_u32_e32 v193, 0xfffffb80, v192
	v_add_u32_e32 v194, 0x4800, v0
	v_add_u32_e32 v197, 0xd400, v0
	v_add_u32_e32 v199, 0x8c00, v196
	v_mad_u32_u24 v202, v171, s37, 0
	v_mov_b32_e32 v179, v1
	v_lshlrev_b32_e32 v180, 1, v2
	v_mov_b32_e32 v181, v1
	s_mov_b32 s36, 0xf0f0f0f1
	s_movk_i32 s37, 0xffef
	s_movk_i32 s38, 0x490
	s_mov_b32 s39, 0x38e38e39
	v_readlane_b32 s42, v251, 39
	v_writelane_b32 v250, s94, 15
	v_writelane_b32 v250, s95, 16
	s_mov_b32 s99, 0
; __device__ __forceinline__ bool attn_unit(const Ptrs& P, LAS unsigned char* lds, int unit, int tid, int wave, int lane, bool pre, int nxt) {
;     const int n = unit & 31, kh = (unit >> 5) & 3, b = unit >> 7;
;     const int g = wave & 3, q0 = 64 * (wave >> 2), h = kh * 4 + g, r = lane & 31, hh = lane >> 5;
;     unsigned char* ws = P.ws;
;     bf16_t* Qb = (bf16_t*)(ws + WS_Q) + (size_t)(b * SEQ + n * 128 + q0) * DM + h * 64;
;     const bf16_t* Kg = (const bf16_t*)(ws + WS_K) + (size_t)b * SEQ * KVW + kh * 64; const bf16_t* Vg = (const bf16_t*)(ws + WS_VT) + (size_t)(b * 4 + kh) * 64 * SEQ;
;     const bf16_t* Kcg = (const bf16_t*)(ws + WS_KC) + (size_t)b * CTX * KVW + kh * 64; const bf16_t* Vcg = (const bf16_t*)(ws + WS_VCT) + (size_t)(b * 4 + kh) * 64 * CTX;
;     float mq = fabsf(P.qg[lane]), mk = fabsf(P.kg[lane]);
; #pragma unroll
;     for (int o = 1; o < 64; o <<= 1) { mq = fmaxf(mq, __shfl_xor(mq, o)); mk = fmaxf(mk, __shfl_xor(mk, o)); }
;     const float sink2 = P.sink[h] * LOG2E; const float mshift = fmaxf(64.0f * QSCALE * mq * mk, sink2);
;     bf16x8_t qf[2][4];
; #pragma unroll
;     for (int cb = 0; cb < 2; ++cb)
; #pragma unroll
;         for (int ds = 0; ds < 4; ++ds) qf[cb][ds] = __builtin_nontemporal_load((const bf16x8_t*)(Qb + (size_t)(32 * cb + r) * DM + 16 * ds + 8 * hh));
.LBB9_308:
	s_and_b32 s43, s42, 31
	s_ashr_i32 s82, s42, 7
	s_lshl_b32 s47, s43, 7
	s_lshl_b32 s46, s82, 12
	s_add_i32 s70, s47, s33
	s_add_i32 s50, s70, s46
	s_bfe_u32 s44, s42, 0x20005
	s_mov_b32 s46, s50
	s_lshl_b32 s45, s44, 2
	s_ashr_i32 s83, s82, 31
	v_readlane_b32 s48, v251, 40
	s_ashr_i32 s51, s50, 31
	v_writelane_b32 v250, s46, 17
	s_or_b32 s45, s45, s48
	s_lshl_b64 s[48:49], s[82:83], 21
	v_writelane_b32 v250, s47, 18
	s_lshl_b64 s[78:79], s[50:51], 11
	v_readlane_b32 s46, v251, 59
	s_add_u32 s46, s46, s48
	v_readlane_b32 s48, v251, 60
	s_addc_u32 s48, s48, s49
	s_lshl_b32 s49, s44, 7
	s_add_u32 s96, s46, s49
	s_addc_u32 s97, s48, 0
	s_lshl_b32 s46, s82, 2
	s_or_b32 s70, s46, s44
	s_ashr_i32 s71, s70, 31
	s_lshl_b64 s[74:75], s[70:71], 19
	v_readlane_b32 s46, v251, 63
	s_add_u32 s46, s46, s78
	v_readlane_b32 s48, v250, 0
	s_addc_u32 s49, s48, s79
	s_lshl_b32 s48, s45, 7
	s_add_u32 s48, s46, s48
	s_addc_u32 s49, s49, 0
	s_mov_b64 s[88:89], s[72:73]
	s_mov_b64 s[80:81], s[34:35]
	s_mov_b64 s[34:35], s[30:31]
	s_mov_b64 s[30:31], s[28:29]
	s_mov_b64 s[28:29], s[26:27]
	s_mov_b64 s[26:27], s[24:25]
	s_mov_b64 s[24:25], s[22:23]
	s_mov_b64 s[22:23], s[20:21]
	s_mov_b64 s[20:21], s[18:19]
	s_mov_b64 s[18:19], s[16:17]
	s_mov_b64 s[16:17], s[14:15]
	s_mov_b64 s[14:15], s[12:13]
	s_mov_b64 s[12:13], s[10:11]
	s_mov_b64 s[10:11], s[8:9]
	s_mov_b64 s[8:9], s[6:7]
	s_mov_b64 s[6:7], s[4:5]
	s_mov_b64 s[4:5], s[0:1]
	s_mov_b64 s[0:1], s[66:67]
	s_mov_b64 s[40:41], s[64:65]
	s_mov_b64 s[66:67], s[62:63]
	s_mov_b64 s[64:65], s[60:61]
	s_mov_b64 s[72:73], s[56:57]
	s_lshl_b32 s46, s45, 2
	v_lshl_add_u64 v[4:5], s[48:49], 0, v[178:179]
	s_mov_b64 s[78:79], s[54:55]
	v_readlane_b32 s48, v251, 16
	v_mov_b32_e32 v3, s46
	v_readlane_b32 s56, v251, 24
	v_readlane_b32 s57, v251, 25
	v_lshl_add_u64 v[4:5], v[4:5], 0, v[180:181]
	v_readlane_b32 s51, v251, 19
	v_readlane_b32 s46, v250, 1
	v_readlane_b32 s50, v251, 18
	v_readlane_b32 s54, v251, 22
	s_cmp_eq_u32 s99, 1
	s_cbranch_scc1 .Lqh_a
	global_load_dword v0, v[172:173], off
	global_load_dword v2, v[174:175], off
	global_load_dword v3, v3, s[56:57]
	s_nop 0
	global_load_dwordx4 v[114:117], v[4:5], off nt
	global_load_dwordx4 v[118:121], v[4:5], off offset:32 nt
	global_load_dwordx4 v[122:125], v[4:5], off offset:64 nt
	global_load_dwordx4 v[126:129], v[4:5], off offset:96 nt
	v_add_co_u32_e32 v4, vcc, 0x10000, v4
	v_readlane_b32 s55, v251, 23
	s_nop 0
	v_addc_co_u32_e32 v5, vcc, 0, v5, vcc
	global_load_dwordx4 v[130:133], v[4:5], off nt
	global_load_dwordx4 v[134:137], v[4:5], off offset:32 nt
	global_load_dwordx4 v[138:141], v[4:5], off offset:64 nt
	global_load_dwordx4 v[142:145], v[4:5], off offset:96 nt
	s_add_u32 s51, s46, s74
	s_waitcnt vmcnt(9)
	s_branch .Lqh_j
.Lqh_a:
	v_readlane_b32 s55, v251, 23
	s_add_u32 s51, s46, s74
	s_waitcnt vmcnt(17)
	v_mov_b32_e32 v0, v254
	v_mov_b32_e32 v2, v255
.Lqh_j:
	v_and_b32_e32 v4, 0x7fffffff, v0
	v_and_b32_e32 v5, 0x7fffffff, v2
	ds_bpermute_b32 v4, v185, v4
	ds_bpermute_b32 v5, v185, v5
	v_max_f32_e64 v0, |v0|, |v0|
	v_max_f32_e64 v2, |v2|, |v2|
	v_readlane_b32 s46, v250, 2
	s_waitcnt lgkmcnt(1)
	v_max_f32_e32 v4, v4, v4
	s_waitcnt lgkmcnt(0)
	v_max_f32_e32 v5, v5, v5
	v_max_f32_e32 v0, v0, v4
	v_max_f32_e32 v2, v2, v5
	ds_bpermute_b32 v4, v186, v0
	ds_bpermute_b32 v5, v186, v2
	s_mov_b64 s[54:55], s[78:79]
	v_readlane_b32 s50, v251, 32
	s_addc_u32 s46, s46, s75
	s_waitcnt lgkmcnt(1)
	v_max_f32_e32 v4, v4, v4
	s_waitcnt lgkmcnt(0)
	v_max_f32_e32 v5, v5, v5
	v_max_f32_e32 v0, v0, v4
	v_max_f32_e32 v2, v2, v5
	ds_bpermute_b32 v4, v187, v0
	ds_bpermute_b32 v5, v187, v2
	s_and_b64 vcc, exec, s[68:69]
	v_readlane_b32 s49, v251, 17
	v_readlane_b32 s52, v251, 20
	s_waitcnt lgkmcnt(1)
	v_max_f32_e32 v4, v4, v4
	s_waitcnt lgkmcnt(0)
	v_max_f32_e32 v5, v5, v5
	v_max_f32_e32 v0, v0, v4
	v_max_f32_e32 v2, v2, v5
	ds_bpermute_b32 v4, v188, v0
	ds_bpermute_b32 v5, v188, v2
	v_readlane_b32 s53, v251, 21
	v_readlane_b32 s58, v251, 26
	v_readlane_b32 s59, v251, 27
	s_waitcnt lgkmcnt(1)
	v_max_f32_e32 v4, v4, v4
	s_waitcnt lgkmcnt(0)
	v_max_f32_e32 v5, v5, v5
	v_max_f32_e32 v0, v0, v4
	v_max_f32_e32 v2, v2, v5
	ds_bpermute_b32 v4, v189, v0
	ds_bpermute_b32 v5, v189, v2
	v_readlane_b32 s60, v251, 28
	v_readlane_b32 s61, v251, 29
	v_readlane_b32 s62, v251, 30
	s_waitcnt lgkmcnt(1)
	v_max_f32_e32 v4, v4, v4
	s_waitcnt lgkmcnt(0)
	v_max_f32_e32 v5, v5, v5
	v_max_f32_e32 v9, v0, v4
	v_max_f32_e32 v8, v2, v5
	ds_bpermute_b32 v11, v190, v9
	ds_bpermute_b32 v10, v190, v8
	v_readlane_b32 s63, v251, 31
	s_cbranch_vccnz .LBB9_329
	s_lshl_b32 s99, s99, 1
	s_cmp_lg_u32 s43, 0
	s_cbranch_scc0 .LBB9_319
	s_andn2_b64 vcc, exec, s[54:55]
	s_cbranch_vccnz .LBB9_318
	s_add_i32 s76, s43, -1
	s_lshl_b64 s[48:49], s[76:77], 16
	s_add_u32 s68, s96, s48
	s_addc_u32 s69, s97, s49
	s_lshl_b32 s48, s76, 8
	s_add_u32 s84, s51, s48
	s_addc_u32 s85, s46, 0
	v_mov_b32_e32 v12, v193
	v_mov_b32_e32 v2, v192
	s_mov_b32 s76, s50
	s_branch .LBB9_314

; #define AT_SYNC() do { asm volatile("s_waitcnt vmcnt(0) lgkmcnt(0)" ::: "memory"); __builtin_amdgcn_s_barrier(); asm volatile("" ::: "memory"); } while (0)
; __device__ __forceinline__ bool attn_unit(const Ptrs& P, LAS unsigned char* lds, int unit, int tid, int wave, int lane, bool pre, int nxt) {
;     ...
;     const float sink2 = P.sink[h] * LOG2E; const float mshift = fmaxf(64.0f * QSCALE * mq * mk, sink2);
;     bf16x8_t qf[2][4];
; #pragma unroll
;     for (int cb = 0; cb < 2; ++cb)
; #pragma unroll
;         for (int ds = 0; ds < 4; ++ds) qf[cb][ds] = __builtin_nontemporal_load((const bf16x8_t*)(Qb + (size_t)(32 * cb + r) * DM + 16 * ds + 8 * hh));
;     f32x16 o[2][2];
; #pragma unroll
;     for (int db = 0; db < 2; ++db)
; #pragma unroll
;         for (int cb = 0; cb < 2; ++cb)
; #pragma unroll
;             for (int i = 0; i < 16; ++i) o[db][cb][i] = 0.f;
;     float rs[2] = {0.f, 0.f};
;     f32x16 negm;
; #pragma unroll
;     for (int i = 0; i < 16; ++i) negm[i] = -mshift;
;     ...
;     if (!pre) { if (n == 0) AT_DMA(1); else AT_DMA(0); }
;     AT_SYNC();
.LBB9_329:
	s_cmp_eq_u32 s99, 0
	s_cbranch_scc0 .Lqh_b
	s_waitcnt vmcnt(8) lgkmcnt(0)
	s_branch .Lqh_bj
.Lqh_b:
	s_waitcnt vmcnt(16) lgkmcnt(0)
	v_mov_b32_e32 v3, v253
.Lqh_bj:
	v_max_f32_e32 v0, v11, v11
	v_max_f32_e32 v2, v9, v9
	v_max_f32_e32 v0, v2, v0
	v_max_f32_e32 v2, v10, v10
	v_max_f32_e32 v4, v8, v8
	v_max_f32_e32 v2, v4, v2
	v_mul_f32_e32 v0, 0x4138aa3b, v0
	v_mul_f32_e32 v0, v2, v0
	v_mul_f32_e32 v177, 0x3fb8aa3b, v3
	v_max_f32_e32 v203, v0, v177
	s_cmp_eq_u32 s99, 1
	s_cbranch_scc1 .Lqh_c
	s_waitcnt vmcnt(0)
.Lqh_c:
	s_waitcnt vmcnt(8) lgkmcnt(0)
	s_mov_b32 s99, 0
	s_barrier
	v_xor_b32_e32 v18, 0x80000000, v203
	v_cndmask_b32_e64 v0, 0, 1, s[54:55]
	v_mov_b32_e32 v19, v18
	v_mov_b32_e32 v20, v18
	v_mov_b32_e32 v21, v18
	v_mov_b32_e32 v22, v18
	v_mov_b32_e32 v23, v18
	v_mov_b32_e32 v24, v18
	v_mov_b32_e32 v25, v18
	v_mov_b32_e32 v26, v18
	v_mov_b32_e32 v27, v18
	v_mov_b32_e32 v28, v18
	v_mov_b32_e32 v29, v18
	v_mov_b32_e32 v30, v18
	v_mov_b32_e32 v31, v18
	v_mov_b32_e32 v32, v18
	v_mov_b32_e32 v33, v18
	s_cmp_eq_u32 s43, 0
	v_cmp_ne_u32_e64 s[68:69], 1, v0
	s_cbranch_scc1 .LBB9_350
	s_mov_b64 s[56:57], s[72:73]
	s_mov_b64 s[72:73], s[88:89]
	v_readlane_b32 s88, v250, 9
	s_and_b64 vcc, exec, s[68:69]
	s_mov_b64 s[60:61], s[64:65]
	s_mov_b64 s[62:63], s[66:67]
	s_mov_b64 s[64:65], s[40:41]
	s_mov_b64 s[66:67], s[0:1]
	s_mov_b64 s[0:1], s[4:5]
	s_mov_b64 s[4:5], s[6:7]
	s_mov_b64 s[6:7], s[8:9]
	s_mov_b64 s[8:9], s[10:11]
	s_mov_b64 s[10:11], s[12:13]
	s_mov_b64 s[12:13], s[14:15]
	s_mov_b64 s[14:15], s[16:17]
	s_mov_b64 s[16:17], s[18:19]
	s_mov_b64 s[18:19], s[20:21]
	s_mov_b64 s[20:21], s[22:23]
	s_mov_b64 s[22:23], s[24:25]
	s_mov_b64 s[24:25], s[26:27]
	s_mov_b64 s[26:27], s[28:29]
	s_mov_b64 s[28:29], s[30:31]
	s_mov_b64 s[30:31], s[34:35]
	s_mov_b64 s[34:35], s[80:81]
	v_readlane_b32 s89, v250, 10
	v_readlane_b32 s90, v250, 11
	v_readlane_b32 s91, v250, 12
	v_readlane_b32 s92, v250, 13
	v_readlane_b32 s93, v250, 14
	v_readlane_b32 s94, v250, 15
	v_readlane_b32 s95, v250, 16
	s_cbranch_vccnz .LBB9_338
	s_lshl_b32 s48, s43, 16
	s_add_u32 s84, s96, s48
	s_addc_u32 s85, s97, 0
	s_lshl_b32 s47, s47, 1
	s_add_u32 s74, s51, s47
	s_addc_u32 s75, s46, 0
	v_mov_b32_e32 v3, v193
	v_mov_b32_e32 v2, v192
	s_mov_b32 s47, s50
	s_branch .LBB9_334

; __device__ __forceinline__ unsigned cvtpk(float lo, float hi) { f32x2_t v = {lo, hi}; bf16x2_t b = __builtin_convertvector(v, bf16x2_t); return __builtin_bit_cast(unsigned, b); }
; #define LAS __attribute__((address_space(3)))
; __device__ __forceinline__ bool attn_unit(const Ptrs& P, LAS unsigned char* lds, int unit, int tid, int wave, int lane, bool pre, int nxt) {
;     ...
;         for (int kt = 0; kt < 4; ++kt) {
;             if (c == 0 && 32 * kt + 31 < q0) continue;
;             if (c == 2 && 32 * kt > q0 + 63) continue;
;             bf16x8_t kf[4], vf[2][2];
; #pragma unroll
;             for (int ds = 0; ds < 4; ++ds) kf[ds] = *(const LAS bf16x8_t*)(Kl + (32 * kt + r) * AT_KP + (16 * ds + 8 * hh) * 2);
; #pragma unroll
;             for (int db = 0; db < 2; ++db)
; #pragma unroll
;                 for (int s = 0; s < 2; ++s) vf[db][s] = *(const LAS bf16x8_t*)(Vl + (32 * db + r) * AT_VP + (32 * kt + 16 * s + 8 * hh) * 2);
; #pragma unroll
;             for (int cb = 0; cb < 2; ++cb) {
;                 const int dq = 32 * kt - (q0 + 32 * cb);
;                 if ((c == 0 && dq < 0) || (c == 2 && dq > 0)) continue;
;                 const bool diag = (c == 0 || c == 2) && dq == 0;
;                 f32x16 st = MFMA32(kf[0], qf[cb][0], negm);
;                 st = MFMA32(kf[1], qf[cb][1], st); st = MFMA32(kf[2], qf[cb][2], st); st = MFMA32(kf[3], qf[cb][3], st);
;                 float p[16];
; #pragma unroll
;                 for (int i = 0; i < 16; ++i) p[i] = __builtin_amdgcn_exp2f(st[i]);
;                 if (diag) {
;                     const int thr = r - 4 * hh;
; #pragma unroll
;                     for (int i = 0; i < 16; ++i) { const bool vis = c == 0 ? crow(i, 0) >= thr : crow(i, 0) <= thr; p[i] = vis ? p[i] : 0.f; }
;                 }
;                 float s4 = 0.f;
; #pragma unroll
;                 for (int i = 0; i < 16; ++i) s4 += p[i];
;                 rs[cb] += s4;
; #pragma unroll
;                 for (int s = 0; s < 2; ++s) {
;                     u32x4 w; w.x = cvtpk(p[8 * s], p[8 * s + 1]); w.y = cvtpk(p[8 * s + 2], p[8 * s + 3]); w.z = cvtpk(p[8 * s + 4], p[8 * s + 5]); w.w = cvtpk(p[8 * s + 6], p[8 * s + 7]);
;                     const bf16x8_t pb = __builtin_bit_cast(bf16x8_t, w);
;                     o[0][cb] = MFMA32(vf[0][s], pb, o[0][cb]); o[1][cb] = MFMA32(vf[1][s], pb, o[1][cb]);
;                 }
.LBB9_411:
	ds_read_b128 v[238:241], v199 offset:0
	ds_read_b128 v[242:245], v199 offset:32
	ds_read_b128 v[246:249], v199 offset:64
	ds_read_b128 v[204:207], v199 offset:96
	s_waitcnt lgkmcnt(0)
	v_mfma_f32_32x32x16_bf16 v[82:97], v[238:241], v[114:117], v[18:33]
	v_mfma_f32_32x32x16_bf16 v[82:97], v[242:245], v[118:121], v[82:97]
	v_mfma_f32_32x32x16_bf16 v[82:97], v[246:249], v[122:125], v[82:97]
	v_mfma_f32_32x32x16_bf16 v[82:97], v[204:207], v[126:129], v[82:97]
	v_mfma_f32_32x32x16_bf16 v[98:113], v[238:241], v[130:133], v[18:33]
	v_mfma_f32_32x32x16_bf16 v[98:113], v[242:245], v[134:137], v[98:113]
	v_mfma_f32_32x32x16_bf16 v[98:113], v[246:249], v[138:141], v[98:113]
	v_mfma_f32_32x32x16_bf16 v[98:113], v[204:207], v[142:145], v[98:113]
	ds_read_b128 v[146:149], v198 offset:0
	ds_read_b128 v[150:153], v198 offset:32
	ds_read_b128 v[154:157], v197 offset:0
	ds_read_b128 v[158:161], v197 offset:32
	ds_read_b128 v[238:241], v199 offset:4608
	ds_read_b128 v[242:245], v199 offset:4640
	ds_read_b128 v[246:249], v199 offset:4672
	ds_read_b128 v[204:207], v199 offset:4704
	v_exp_f32_e32 v82, v82
	v_exp_f32_e32 v83, v83
	v_exp_f32_e32 v84, v84
	v_exp_f32_e32 v85, v85
	v_exp_f32_e32 v86, v86
	v_exp_f32_e32 v87, v87
	v_exp_f32_e32 v88, v88
	v_exp_f32_e32 v89, v89
	v_exp_f32_e32 v90, v90
	v_exp_f32_e32 v91, v91
	v_exp_f32_e32 v92, v92
	v_exp_f32_e32 v93, v93
	v_exp_f32_e32 v94, v94
	v_exp_f32_e32 v95, v95
	v_exp_f32_e32 v96, v96
	v_exp_f32_e32 v97, v97
	v_add_f32_e32 v183, v82, v183
	v_add_f32_e32 v183, v83, v183
	v_add_f32_e32 v183, v84, v183
	v_add_f32_e32 v183, v85, v183
	v_add_f32_e32 v183, v86, v183
	v_add_f32_e32 v183, v87, v183
	v_add_f32_e32 v183, v88, v183
	v_add_f32_e32 v183, v89, v183
	v_add_f32_e32 v183, v90, v183
	v_add_f32_e32 v183, v91, v183
	v_add_f32_e32 v183, v92, v183
	v_add_f32_e32 v183, v93, v183
	v_add_f32_e32 v183, v94, v183
	v_add_f32_e32 v183, v95, v183
	v_add_f32_e32 v183, v96, v183
	v_add_f32_e32 v183, v97, v183
	v_cvt_pk_bf16_f32 v82, v82, v83
	v_cvt_pk_bf16_f32 v83, v84, v85
	v_cvt_pk_bf16_f32 v84, v86, v87
	v_cvt_pk_bf16_f32 v85, v88, v89
	v_cvt_pk_bf16_f32 v86, v90, v91
	v_cvt_pk_bf16_f32 v87, v92, v93
	v_cvt_pk_bf16_f32 v88, v94, v95
	v_cvt_pk_bf16_f32 v89, v96, v97
	s_nop 0
	s_waitcnt lgkmcnt(4)
	v_mfma_f32_32x32x16_bf16 v[66:81], v[146:149], v[82:85], v[66:81]
	v_mfma_f32_32x32x16_bf16 v[50:65], v[154:157], v[82:85], v[50:65]
	v_exp_f32_e32 v98, v98
	v_exp_f32_e32 v99, v99
	v_exp_f32_e32 v100, v100
	v_exp_f32_e32 v101, v101
	v_exp_f32_e32 v102, v102
	v_mfma_f32_32x32x16_bf16 v[66:81], v[150:153], v[86:89], v[66:81]
	v_exp_f32_e32 v103, v103
	v_exp_f32_e32 v104, v104
	v_exp_f32_e32 v105, v105
	v_exp_f32_e32 v106, v106
	v_exp_f32_e32 v107, v107
	v_mfma_f32_32x32x16_bf16 v[50:65], v[158:161], v[86:89], v[50:65]
	v_exp_f32_e32 v108, v108
	v_exp_f32_e32 v109, v109
	v_exp_f32_e32 v110, v110
	v_exp_f32_e32 v111, v111
	v_exp_f32_e32 v112, v112
	s_waitcnt lgkmcnt(0)
	v_mfma_f32_32x32x16_bf16 v[82:97], v[238:241], v[114:117], v[18:33]
	v_exp_f32_e32 v113, v113
	v_add_f32_e32 v182, v98, v182
	v_add_f32_e32 v182, v99, v182
	v_add_f32_e32 v182, v100, v182
	v_add_f32_e32 v182, v101, v182
	v_mfma_f32_32x32x16_bf16 v[82:97], v[242:245], v[118:121], v[82:97]
	v_add_f32_e32 v182, v102, v182
	v_add_f32_e32 v182, v103, v182
	v_add_f32_e32 v182, v104, v182
	v_add_f32_e32 v182, v105, v182
	v_add_f32_e32 v182, v106, v182
	v_mfma_f32_32x32x16_bf16 v[82:97], v[246:249], v[122:125], v[82:97]
	v_add_f32_e32 v182, v107, v182
	v_add_f32_e32 v182, v108, v182
	v_add_f32_e32 v182, v109, v182
	v_add_f32_e32 v182, v110, v182
	v_add_f32_e32 v182, v111, v182
	v_mfma_f32_32x32x16_bf16 v[82:97], v[204:207], v[126:129], v[82:97]
	v_add_f32_e32 v182, v112, v182
	v_add_f32_e32 v182, v113, v182
	v_cvt_pk_bf16_f32 v98, v98, v99
	v_cvt_pk_bf16_f32 v99, v100, v101
	v_cvt_pk_bf16_f32 v100, v102, v103
	v_cvt_pk_bf16_f32 v101, v104, v105
	v_cvt_pk_bf16_f32 v102, v106, v107
	v_cvt_pk_bf16_f32 v103, v108, v109
	v_cvt_pk_bf16_f32 v104, v110, v111
	v_cvt_pk_bf16_f32 v105, v112, v113
	s_nop 0
	v_mfma_f32_32x32x16_bf16 v[34:49], v[146:149], v[98:101], v[34:49]
	v_mfma_f32_32x32x16_bf16 v[2:17], v[154:157], v[98:101], v[2:17]
	v_exp_f32_e32 v82, v82
	v_exp_f32_e32 v83, v83
	v_exp_f32_e32 v84, v84
	v_exp_f32_e32 v85, v85
	v_exp_f32_e32 v86, v86
	v_mfma_f32_32x32x16_bf16 v[34:49], v[150:153], v[102:105], v[34:49]
	v_exp_f32_e32 v87, v87
	v_exp_f32_e32 v88, v88
	v_exp_f32_e32 v89, v89
	v_exp_f32_e32 v90, v90
	v_exp_f32_e32 v91, v91
	v_mfma_f32_32x32x16_bf16 v[2:17], v[158:161], v[102:105], v[2:17]
	ds_read_b128 v[146:149], v198 offset:64
	ds_read_b128 v[150:153], v198 offset:96
	ds_read_b128 v[154:157], v197 offset:64
	ds_read_b128 v[158:161], v197 offset:96
	v_exp_f32_e32 v92, v92
	v_exp_f32_e32 v93, v93
	v_exp_f32_e32 v94, v94
	v_exp_f32_e32 v95, v95
	v_exp_f32_e32 v96, v96
	v_mfma_f32_32x32x16_bf16 v[98:113], v[238:241], v[130:133], v[18:33]
	v_exp_f32_e32 v97, v97
	v_add_f32_e32 v183, v82, v183
	v_add_f32_e32 v183, v83, v183
	v_add_f32_e32 v183, v84, v183
	v_add_f32_e32 v183, v85, v183
	v_mfma_f32_32x32x16_bf16 v[98:113], v[242:245], v[134:137], v[98:113]
	v_add_f32_e32 v183, v86, v183
	v_add_f32_e32 v183, v87, v183
	v_add_f32_e32 v183, v88, v183
	v_add_f32_e32 v183, v89, v183
	v_add_f32_e32 v183, v90, v183
	v_mfma_f32_32x32x16_bf16 v[98:113], v[246:249], v[138:141], v[98:113]
	v_add_f32_e32 v183, v91, v183
	v_add_f32_e32 v183, v92, v183
	v_add_f32_e32 v183, v93, v183
	v_add_f32_e32 v183, v94, v183
	v_add_f32_e32 v183, v95, v183
	v_mfma_f32_32x32x16_bf16 v[98:113], v[204:207], v[142:145], v[98:113]
	ds_read_b128 v[238:241], v199 offset:9216
	ds_read_b128 v[242:245], v199 offset:9248
	ds_read_b128 v[246:249], v199 offset:9280
	ds_read_b128 v[204:207], v199 offset:9312
	v_add_f32_e32 v183, v96, v183
	v_add_f32_e32 v183, v97, v183
	v_cvt_pk_bf16_f32 v82, v82, v83
	v_cvt_pk_bf16_f32 v83, v84, v85
	v_cvt_pk_bf16_f32 v84, v86, v87
	v_cvt_pk_bf16_f32 v85, v88, v89
	v_cvt_pk_bf16_f32 v86, v90, v91
	v_cvt_pk_bf16_f32 v87, v92, v93
	v_cvt_pk_bf16_f32 v88, v94, v95
	v_cvt_pk_bf16_f32 v89, v96, v97
	s_nop 0
	s_waitcnt lgkmcnt(4)
; __device__ __forceinline__ unsigned cvtpk(float lo, float hi) { f32x2_t v = {lo, hi}; bf16x2_t b = __builtin_convertvector(v, bf16x2_t); return __builtin_bit_cast(unsigned, b); }
; #define LAS __attribute__((address_space(3)))
; __device__ __forceinline__ bool attn_unit(const Ptrs& P, LAS unsigned char* lds, int unit, int tid, int wave, int lane, bool pre, int nxt) {
;     ...
;         for (int kt = 0; kt < 4; ++kt) {
;             if (c == 0 && 32 * kt + 31 < q0) continue;
;             if (c == 2 && 32 * kt > q0 + 63) continue;
;             bf16x8_t kf[4], vf[2][2];
; #pragma unroll
;             for (int ds = 0; ds < 4; ++ds) kf[ds] = *(const LAS bf16x8_t*)(Kl + (32 * kt + r) * AT_KP + (16 * ds + 8 * hh) * 2);
; #pragma unroll
;             for (int db = 0; db < 2; ++db)
; #pragma unroll
;                 for (int s = 0; s < 2; ++s) vf[db][s] = *(const LAS bf16x8_t*)(Vl + (32 * db + r) * AT_VP + (32 * kt + 16 * s + 8 * hh) * 2);
; #pragma unroll
;             for (int cb = 0; cb < 2; ++cb) {
;                 const int dq = 32 * kt - (q0 + 32 * cb);
;                 if ((c == 0 && dq < 0) || (c == 2 && dq > 0)) continue;
;                 const bool diag = (c == 0 || c == 2) && dq == 0;
;                 f32x16 st = MFMA32(kf[0], qf[cb][0], negm);
;                 st = MFMA32(kf[1], qf[cb][1], st); st = MFMA32(kf[2], qf[cb][2], st); st = MFMA32(kf[3], qf[cb][3], st);
;                 float p[16];
; #pragma unroll
;                 for (int i = 0; i < 16; ++i) p[i] = __builtin_amdgcn_exp2f(st[i]);
;                 if (diag) {
;                     const int thr = r - 4 * hh;
; #pragma unroll
;                     for (int i = 0; i < 16; ++i) { const bool vis = c == 0 ? crow(i, 0) >= thr : crow(i, 0) <= thr; p[i] = vis ? p[i] : 0.f; }
;                 }
;                 float s4 = 0.f;
; #pragma unroll
;                 for (int i = 0; i < 16; ++i) s4 += p[i];
;                 rs[cb] += s4;
; #pragma unroll
;                 for (int s = 0; s < 2; ++s) {
;                     u32x4 w; w.x = cvtpk(p[8 * s], p[8 * s + 1]); w.y = cvtpk(p[8 * s + 2], p[8 * s + 3]); w.z = cvtpk(p[8 * s + 4], p[8 * s + 5]); w.w = cvtpk(p[8 * s + 6], p[8 * s + 7]);
;                     const bf16x8_t pb = __builtin_bit_cast(bf16x8_t, w);
;                     o[0][cb] = MFMA32(vf[0][s], pb, o[0][cb]); o[1][cb] = MFMA32(vf[1][s], pb, o[1][cb]);
;                 }
	v_mfma_f32_32x32x16_bf16 v[66:81], v[146:149], v[82:85], v[66:81]
	v_mfma_f32_32x32x16_bf16 v[50:65], v[154:157], v[82:85], v[50:65]
	v_exp_f32_e32 v98, v98
	v_exp_f32_e32 v99, v99
	v_exp_f32_e32 v100, v100
	v_exp_f32_e32 v101, v101
	v_exp_f32_e32 v102, v102
	v_mfma_f32_32x32x16_bf16 v[66:81], v[150:153], v[86:89], v[66:81]
	v_exp_f32_e32 v103, v103
	v_exp_f32_e32 v104, v104
	v_exp_f32_e32 v105, v105
	v_exp_f32_e32 v106, v106
	v_exp_f32_e32 v107, v107
	v_mfma_f32_32x32x16_bf16 v[50:65], v[158:161], v[86:89], v[50:65]
	v_exp_f32_e32 v108, v108
	v_exp_f32_e32 v109, v109
	v_exp_f32_e32 v110, v110
	v_exp_f32_e32 v111, v111
	v_exp_f32_e32 v112, v112
	s_waitcnt lgkmcnt(0)
	v_mfma_f32_32x32x16_bf16 v[82:97], v[238:241], v[114:117], v[18:33]
	v_exp_f32_e32 v113, v113
	v_add_f32_e32 v182, v98, v182
	v_add_f32_e32 v182, v99, v182
	v_add_f32_e32 v182, v100, v182
	v_add_f32_e32 v182, v101, v182
	v_mfma_f32_32x32x16_bf16 v[82:97], v[242:245], v[118:121], v[82:97]
	v_add_f32_e32 v182, v102, v182
	v_add_f32_e32 v182, v103, v182
	v_add_f32_e32 v182, v104, v182
	v_add_f32_e32 v182, v105, v182
	v_add_f32_e32 v182, v106, v182
	v_mfma_f32_32x32x16_bf16 v[82:97], v[246:249], v[122:125], v[82:97]
	v_add_f32_e32 v182, v107, v182
	v_add_f32_e32 v182, v108, v182
	v_add_f32_e32 v182, v109, v182
	v_add_f32_e32 v182, v110, v182
	v_add_f32_e32 v182, v111, v182
	v_mfma_f32_32x32x16_bf16 v[82:97], v[204:207], v[126:129], v[82:97]
	v_add_f32_e32 v182, v112, v182
	v_add_f32_e32 v182, v113, v182
	v_cvt_pk_bf16_f32 v98, v98, v99
	v_cvt_pk_bf16_f32 v99, v100, v101
	v_cvt_pk_bf16_f32 v100, v102, v103
	v_cvt_pk_bf16_f32 v101, v104, v105
	v_cvt_pk_bf16_f32 v102, v106, v107
	v_cvt_pk_bf16_f32 v103, v108, v109
	v_cvt_pk_bf16_f32 v104, v110, v111
	v_cvt_pk_bf16_f32 v105, v112, v113
	s_nop 0
	v_mfma_f32_32x32x16_bf16 v[34:49], v[146:149], v[98:101], v[34:49]
	v_mfma_f32_32x32x16_bf16 v[2:17], v[154:157], v[98:101], v[2:17]
	v_exp_f32_e32 v82, v82
	v_exp_f32_e32 v83, v83
	v_exp_f32_e32 v84, v84
	v_exp_f32_e32 v85, v85
	v_exp_f32_e32 v86, v86
	v_mfma_f32_32x32x16_bf16 v[34:49], v[150:153], v[102:105], v[34:49]
	v_exp_f32_e32 v87, v87
	v_exp_f32_e32 v88, v88
	v_exp_f32_e32 v89, v89
	v_exp_f32_e32 v90, v90
	v_exp_f32_e32 v91, v91
	v_mfma_f32_32x32x16_bf16 v[2:17], v[158:161], v[102:105], v[2:17]
	ds_read_b128 v[146:149], v198 offset:128
	ds_read_b128 v[150:153], v198 offset:160
	ds_read_b128 v[154:157], v197 offset:128
	ds_read_b128 v[158:161], v197 offset:160
	v_exp_f32_e32 v92, v92
	v_exp_f32_e32 v93, v93
	v_exp_f32_e32 v94, v94
	v_exp_f32_e32 v95, v95
	v_exp_f32_e32 v96, v96
	v_mfma_f32_32x32x16_bf16 v[98:113], v[238:241], v[130:133], v[18:33]
	v_exp_f32_e32 v97, v97
	v_add_f32_e32 v183, v82, v183
	v_add_f32_e32 v183, v83, v183
	v_add_f32_e32 v183, v84, v183
	v_add_f32_e32 v183, v85, v183
	v_mfma_f32_32x32x16_bf16 v[98:113], v[242:245], v[134:137], v[98:113]
	v_add_f32_e32 v183, v86, v183
	v_add_f32_e32 v183, v87, v183
	v_add_f32_e32 v183, v88, v183
	v_add_f32_e32 v183, v89, v183
	v_add_f32_e32 v183, v90, v183
	v_mfma_f32_32x32x16_bf16 v[98:113], v[246:249], v[138:141], v[98:113]
	v_add_f32_e32 v183, v91, v183
	v_add_f32_e32 v183, v92, v183
	v_add_f32_e32 v183, v93, v183
	v_add_f32_e32 v183, v94, v183
	v_add_f32_e32 v183, v95, v183
	v_mfma_f32_32x32x16_bf16 v[98:113], v[204:207], v[142:145], v[98:113]
	ds_read_b128 v[238:241], v199 offset:13824
	ds_read_b128 v[242:245], v199 offset:13856
	ds_read_b128 v[246:249], v199 offset:13888
	ds_read_b128 v[204:207], v199 offset:13920
	v_add_f32_e32 v183, v96, v183
	v_add_f32_e32 v183, v97, v183
	v_cvt_pk_bf16_f32 v82, v82, v83
	v_cvt_pk_bf16_f32 v83, v84, v85
	v_cvt_pk_bf16_f32 v84, v86, v87
	v_cvt_pk_bf16_f32 v85, v88, v89
	v_cvt_pk_bf16_f32 v86, v90, v91
	v_cvt_pk_bf16_f32 v87, v92, v93
	v_cvt_pk_bf16_f32 v88, v94, v95
	v_cvt_pk_bf16_f32 v89, v96, v97
	s_nop 0
	s_waitcnt lgkmcnt(4)
	v_mfma_f32_32x32x16_bf16 v[66:81], v[146:149], v[82:85], v[66:81]
	v_mfma_f32_32x32x16_bf16 v[50:65], v[154:157], v[82:85], v[50:65]
	v_exp_f32_e32 v98, v98
	v_exp_f32_e32 v99, v99
	v_exp_f32_e32 v100, v100
	v_exp_f32_e32 v101, v101
	v_exp_f32_e32 v102, v102
	v_mfma_f32_32x32x16_bf16 v[66:81], v[150:153], v[86:89], v[66:81]
	v_exp_f32_e32 v103, v103
	v_exp_f32_e32 v104, v104
	v_exp_f32_e32 v105, v105
	v_exp_f32_e32 v106, v106
	v_exp_f32_e32 v107, v107
	v_mfma_f32_32x32x16_bf16 v[50:65], v[158:161], v[86:89], v[50:65]
	v_exp_f32_e32 v108, v108
	v_exp_f32_e32 v109, v109
	v_exp_f32_e32 v110, v110
	v_exp_f32_e32 v111, v111
	v_exp_f32_e32 v112, v112
	s_waitcnt lgkmcnt(0)
; __device__ __forceinline__ int crow(int reg, int h) { return (reg & 3) + 8 * (reg >> 2) + 4 * h; }
; __device__ __forceinline__ bool attn_unit(const Ptrs& P, LAS unsigned char* lds, int unit, int tid, int wave, int lane, bool pre, int nxt) {
;     ...
;             for (int cb = 0; cb < 2; ++cb) {
;                 const int dq = 32 * kt - (q0 + 32 * cb);
;                 if ((c == 0 && dq < 0) || (c == 2 && dq > 0)) continue;
;                 const bool diag = (c == 0 || c == 2) && dq == 0;
;                 f32x16 st = MFMA32(kf[0], qf[cb][0], negm);
;                 st = MFMA32(kf[1], qf[cb][1], st); st = MFMA32(kf[2], qf[cb][2], st); st = MFMA32(kf[3], qf[cb][3], st);
;                 float p[16];
; #pragma unroll
;                 for (int i = 0; i < 16; ++i) p[i] = __builtin_amdgcn_exp2f(st[i]);
;                 if (diag) {
;                     const int thr = r - 4 * hh;
; #pragma unroll
;                     for (int i = 0; i < 16; ++i) { const bool vis = c == 0 ? crow(i, 0) >= thr : crow(i, 0) <= thr; p[i] = vis ? p[i] : 0.f; }
;                 }
;                 float s4 = 0.f;
; #pragma unroll
;                 for (int i = 0; i < 16; ++i) s4 += p[i];
;                 rs[cb] += s4;
; #pragma unroll
;                 for (int s = 0; s < 2; ++s) {
;                     u32x4 w; w.x = cvtpk(p[8 * s], p[8 * s + 1]); w.y = cvtpk(p[8 * s + 2], p[8 * s + 3]); w.z = cvtpk(p[8 * s + 4], p[8 * s + 5]); w.w = cvtpk(p[8 * s + 6], p[8 * s + 7]);
;                     const bf16x8_t pb = __builtin_bit_cast(bf16x8_t, w);
;                     o[0][cb] = MFMA32(vf[0][s], pb, o[0][cb]); o[1][cb] = MFMA32(vf[1][s], pb, o[1][cb]);
;                 }
;             }
;         }
;         AT_SYNC();
;     }
;     ...
;     const float sk = __builtin_amdgcn_exp2f(sink2 - mshift);
; #pragma unroll
;     for (int cb = 0; cb < 2; ++cb) {
;         const float den = rs[cb] + __shfl_xor(rs[cb], 32) + sk; const float inv = __builtin_amdgcn_rcpf(den);
;         bf16_t* orow = (bf16_t*)(ws + WS_ATT) + (size_t)(b * SEQ + n * 128 + q0 + 32 * cb + r) * DM + h * 64;
; #pragma unroll
;         for (int db = 0; db < 2; ++db)
; #pragma unroll
;             for (int p = 0; p < 2; ++p) { u32x2 w0, w1;
;                 w0.x = cvtpk(o[db][cb][8 * p] * inv, o[db][cb][8 * p + 1] * inv); w0.y = cvtpk(o[db][cb][8 * p + 2] * inv, o[db][cb][8 * p + 3] * inv);
	v_mfma_f32_32x32x16_bf16 v[82:97], v[238:241], v[114:117], v[18:33]
	v_exp_f32_e32 v113, v113
	v_add_f32_e32 v182, v98, v182
	v_add_f32_e32 v182, v99, v182
	v_add_f32_e32 v182, v100, v182
	v_add_f32_e32 v182, v101, v182
	v_mfma_f32_32x32x16_bf16 v[82:97], v[242:245], v[118:121], v[82:97]
	v_add_f32_e32 v182, v102, v182
	v_add_f32_e32 v182, v103, v182
	v_add_f32_e32 v182, v104, v182
	v_add_f32_e32 v182, v105, v182
	v_add_f32_e32 v182, v106, v182
	v_mfma_f32_32x32x16_bf16 v[82:97], v[246:249], v[122:125], v[82:97]
	v_add_f32_e32 v182, v107, v182
	v_add_f32_e32 v182, v108, v182
	v_add_f32_e32 v182, v109, v182
	v_add_f32_e32 v182, v110, v182
	v_add_f32_e32 v182, v111, v182
	v_mfma_f32_32x32x16_bf16 v[82:97], v[204:207], v[126:129], v[82:97]
	v_add_f32_e32 v182, v112, v182
	v_add_f32_e32 v182, v113, v182
	v_cvt_pk_bf16_f32 v98, v98, v99
	v_cvt_pk_bf16_f32 v99, v100, v101
	v_cvt_pk_bf16_f32 v100, v102, v103
	v_cvt_pk_bf16_f32 v101, v104, v105
	v_cvt_pk_bf16_f32 v102, v106, v107
	v_cvt_pk_bf16_f32 v103, v108, v109
	v_cvt_pk_bf16_f32 v104, v110, v111
	v_cvt_pk_bf16_f32 v105, v112, v113
	s_nop 0
	v_mfma_f32_32x32x16_bf16 v[34:49], v[146:149], v[98:101], v[34:49]
	v_mfma_f32_32x32x16_bf16 v[2:17], v[154:157], v[98:101], v[2:17]
	v_exp_f32_e32 v82, v82
	v_exp_f32_e32 v83, v83
	v_exp_f32_e32 v84, v84
	v_exp_f32_e32 v85, v85
	v_exp_f32_e32 v86, v86
	v_mfma_f32_32x32x16_bf16 v[34:49], v[150:153], v[102:105], v[34:49]
	v_exp_f32_e32 v87, v87
	v_exp_f32_e32 v88, v88
	v_exp_f32_e32 v89, v89
	v_exp_f32_e32 v90, v90
	v_exp_f32_e32 v91, v91
	v_mfma_f32_32x32x16_bf16 v[2:17], v[158:161], v[102:105], v[2:17]
	ds_read_b128 v[146:149], v198 offset:192
	ds_read_b128 v[150:153], v198 offset:224
	ds_read_b128 v[154:157], v197 offset:192
	ds_read_b128 v[158:161], v197 offset:224
	v_exp_f32_e32 v92, v92
	v_exp_f32_e32 v93, v93
	v_exp_f32_e32 v94, v94
	v_exp_f32_e32 v95, v95
	v_exp_f32_e32 v96, v96
	v_mfma_f32_32x32x16_bf16 v[98:113], v[238:241], v[130:133], v[18:33]
	v_exp_f32_e32 v97, v97
	v_add_f32_e32 v183, v82, v183
	v_add_f32_e32 v183, v83, v183
	v_add_f32_e32 v183, v84, v183
	v_add_f32_e32 v183, v85, v183
	v_mfma_f32_32x32x16_bf16 v[98:113], v[242:245], v[134:137], v[98:113]
	v_add_f32_e32 v183, v86, v183
	v_add_f32_e32 v183, v87, v183
	v_add_f32_e32 v183, v88, v183
	v_add_f32_e32 v183, v89, v183
	v_add_f32_e32 v183, v90, v183
	v_mfma_f32_32x32x16_bf16 v[98:113], v[246:249], v[138:141], v[98:113]
	v_add_f32_e32 v183, v91, v183
	v_add_f32_e32 v183, v92, v183
	v_add_f32_e32 v183, v93, v183
	v_add_f32_e32 v183, v94, v183
	v_add_f32_e32 v183, v95, v183
	v_mfma_f32_32x32x16_bf16 v[98:113], v[204:207], v[142:145], v[98:113]
	v_add_f32_e32 v183, v96, v183
	v_add_f32_e32 v183, v97, v183
	v_cvt_pk_bf16_f32 v82, v82, v83
	v_cvt_pk_bf16_f32 v83, v84, v85
	v_cvt_pk_bf16_f32 v84, v86, v87
	v_cvt_pk_bf16_f32 v85, v88, v89
	v_cvt_pk_bf16_f32 v86, v90, v91
	v_cvt_pk_bf16_f32 v87, v92, v93
	v_cvt_pk_bf16_f32 v88, v94, v95
	v_cvt_pk_bf16_f32 v89, v96, v97
	s_nop 0
	s_waitcnt lgkmcnt(0)
	v_mfma_f32_32x32x16_bf16 v[66:81], v[146:149], v[82:85], v[66:81]
	v_mfma_f32_32x32x16_bf16 v[50:65], v[154:157], v[82:85], v[50:65]
	v_exp_f32_e32 v98, v98
	v_exp_f32_e32 v99, v99
	v_exp_f32_e32 v100, v100
	v_exp_f32_e32 v101, v101
	v_exp_f32_e32 v102, v102
	v_mfma_f32_32x32x16_bf16 v[66:81], v[150:153], v[86:89], v[66:81]
	v_exp_f32_e32 v103, v103
	v_exp_f32_e32 v104, v104
	v_exp_f32_e32 v105, v105
	v_exp_f32_e32 v106, v106
	v_exp_f32_e32 v107, v107
	v_mfma_f32_32x32x16_bf16 v[50:65], v[158:161], v[86:89], v[50:65]
	v_exp_f32_e32 v108, v108
	v_exp_f32_e32 v109, v109
	v_exp_f32_e32 v110, v110
	v_exp_f32_e32 v111, v111
	v_exp_f32_e32 v112, v112
	v_exp_f32_e32 v113, v113
	v_add_f32_e32 v182, v98, v182
	v_add_f32_e32 v182, v99, v182
	v_add_f32_e32 v182, v100, v182
	v_add_f32_e32 v182, v101, v182
	v_add_f32_e32 v182, v102, v182
	v_add_f32_e32 v182, v103, v182
	v_add_f32_e32 v182, v104, v182
	v_add_f32_e32 v182, v105, v182
	v_add_f32_e32 v182, v106, v182
	v_add_f32_e32 v182, v107, v182
	v_add_f32_e32 v182, v108, v182
	v_add_f32_e32 v182, v109, v182
	v_add_f32_e32 v182, v110, v182
	v_add_f32_e32 v182, v111, v182
	v_add_f32_e32 v182, v112, v182
	v_add_f32_e32 v182, v113, v182
	v_cvt_pk_bf16_f32 v98, v98, v99
	v_cvt_pk_bf16_f32 v99, v100, v101
	v_cvt_pk_bf16_f32 v100, v102, v103
	v_cvt_pk_bf16_f32 v101, v104, v105
	v_cvt_pk_bf16_f32 v102, v106, v107
	v_cvt_pk_bf16_f32 v103, v108, v109
	v_cvt_pk_bf16_f32 v104, v110, v111
	v_cvt_pk_bf16_f32 v105, v112, v113
	s_nop 1
	v_mfma_f32_32x32x16_bf16 v[34:49], v[146:149], v[98:101], v[34:49]
	v_mfma_f32_32x32x16_bf16 v[2:17], v[154:157], v[98:101], v[2:17]
	v_mfma_f32_32x32x16_bf16 v[34:49], v[150:153], v[102:105], v[34:49]
	v_mfma_f32_32x32x16_bf16 v[2:17], v[158:161], v[102:105], v[2:17]
	s_movk_i32 s43, 0x100
	v_sub_f32_e32 v0, v177, v203
	v_exp_f32_e32 v28, v0
	ds_bpermute_b32 v0, v190, v183
	v_readlane_b32 s40, v250, 17
	s_lshl_b32 s43, s45, 1
	v_mov_b32_e32 v177, v1
	v_or_b32_e32 v22, s40, v171
	s_waitcnt lgkmcnt(0)
	v_add_f32_e32 v0, v183, v0
	v_add_f32_e32 v0, v28, v0
	v_rcp_f32_e32 v0, v0
	v_readlane_b32 s40, v250, 5
	s_add_u32 s80, s40, s43
	v_readlane_b32 s40, v250, 6
	v_ashrrev_i32_e32 v23, 31, v22
	s_addc_u32 s81, s40, 0
	v_lshlrev_b64 v[18:19], 11, v[22:23]
	v_lshl_add_u64 v[24:25], s[80:81], 0, v[18:19]
	v_pk_mul_f32 v[18:19], v[66:67], v[0:1] op_sel_hi:[1,0]
	v_pk_mul_f32 v[20:21], v[68:69], v[0:1] op_sel_hi:[1,0]
	v_cvt_pk_bf16_f32 v18, v18, v19
	v_cvt_pk_bf16_f32 v19, v20, v21
	v_pk_mul_f32 v[20:21], v[70:71], v[0:1] op_sel_hi:[1,0]
	v_pk_mul_f32 v[26:27], v[72:73], v[0:1] op_sel_hi:[1,0]
	v_cvt_pk_bf16_f32 v20, v20, v21
	v_cvt_pk_bf16_f32 v21, v26, v27
	s_nop 0
	v_permlane32_swap_b32_e32 v18, v20
	v_permlane32_swap_b32_e32 v19, v21
	v_lshl_add_u64 v[24:25], v[24:25], 0, v[176:177]
	s_waitcnt vmcnt(0) lgkmcnt(0)
	s_barrier
; __device__ __forceinline__ unsigned cvtpk(float lo, float hi) { f32x2_t v = {lo, hi}; bf16x2_t b = __builtin_convertvector(v, bf16x2_t); return __builtin_bit_cast(unsigned, b); }
; __device__ __forceinline__ bool attn_unit(const Ptrs& P, LAS unsigned char* lds, int unit, int tid, int wave, int lane, bool pre, int nxt) {
;     ...
;     float mq = fabsf(P.qg[lane]), mk = fabsf(P.kg[lane]);
; #pragma unroll
;     for (int o = 1; o < 64; o <<= 1) { mq = fmaxf(mq, __shfl_xor(mq, o)); mk = fmaxf(mk, __shfl_xor(mk, o)); }
;     const float sink2 = P.sink[h] * LOG2E; const float mshift = fmaxf(64.0f * QSCALE * mq * mk, sink2);
;     bf16x8_t qf[2][4];
; #pragma unroll
;     for (int cb = 0; cb < 2; ++cb)
; #pragma unroll
;         for (int ds = 0; ds < 4; ++ds) qf[cb][ds] = __builtin_nontemporal_load((const bf16x8_t*)(Qb + (size_t)(32 * cb + r) * DM + 16 * ds + 8 * hh));
;     ...
;     const float sk = __builtin_amdgcn_exp2f(sink2 - mshift);
; #pragma unroll
;     for (int cb = 0; cb < 2; ++cb) {
;         const float den = rs[cb] + __shfl_xor(rs[cb], 32) + sk; const float inv = __builtin_amdgcn_rcpf(den);
;         bf16_t* orow = (bf16_t*)(ws + WS_ATT) + (size_t)(b * SEQ + n * 128 + q0 + 32 * cb + r) * DM + h * 64;
; #pragma unroll
;         for (int db = 0; db < 2; ++db)
; #pragma unroll
;             for (int p = 0; p < 2; ++p) { u32x2 w0, w1;
;                 w0.x = cvtpk(o[db][cb][8 * p] * inv, o[db][cb][8 * p + 1] * inv); w0.y = cvtpk(o[db][cb][8 * p + 2] * inv, o[db][cb][8 * p + 3] * inv);
;                 w1.x = cvtpk(o[db][cb][8 * p + 4] * inv, o[db][cb][8 * p + 5] * inv); w1.y = cvtpk(o[db][cb][8 * p + 6] * inv, o[db][cb][8 * p + 7] * inv);
;                 const auto sx = __builtin_amdgcn_permlane32_swap(w0.x, w1.x, false, false), sy = __builtin_amdgcn_permlane32_swap(w0.y, w1.y, false, false);
;                 u32x4 w; w.x = sx[0]; w.y = sy[0]; w.z = sx[1]; w.w = sy[1];
;                 *(u32x4*)(orow + 32 * db + 8 * (2 * p + hh)) = w; }
	s_cmpk_gt_i32 s42, 0x1ff
	s_cbranch_scc1 .Lqh_skip
	global_load_dword v254, v[172:173], off
	global_load_dword v255, v[174:175], off
	s_bfe_u32 s99, s42, 0x20005
	s_lshl_b32 s99, s99, 2
	v_readlane_b32 vcc_lo, v251, 40
	s_and_b32 s98, s42, 31
	s_lshl_b32 s98, s98, 7
	s_add_i32 s98, s98, s33
	s_nop 1
	s_or_b32 s99, s99, vcc_lo
	s_ashr_i32 vcc_lo, s42, 7
	s_lshl_b32 vcc_lo, vcc_lo, 12
	s_add_i32 s98, s98, vcc_lo
	s_lshl_b32 s98, s98, 11
	s_lshl_b32 vcc_lo, s99, 7
	s_add_i32 s98, s98, vcc_lo
	s_lshl_b32 s99, s99, 2
	v_mov_b32_e32 v253, s99
	v_add3_u32 v252, v178, v180, s98
	v_readlane_b32 s98, v251, 24
	v_readlane_b32 s99, v251, 25
	s_nop 4
	global_load_dword v253, v253, s[98:99]
	v_readlane_b32 s98, v251, 63
	v_readlane_b32 s99, v250, 0
	s_nop 4
	global_load_dwordx4 v[114:117], v252, s[98:99] nt
	global_load_dwordx4 v[118:121], v252, s[98:99] offset:32 nt
	global_load_dwordx4 v[122:125], v252, s[98:99] offset:64 nt
	global_load_dwordx4 v[126:129], v252, s[98:99] offset:96 nt
	v_add_u32_e32 v252, 0x10000, v252
	global_load_dwordx4 v[130:133], v252, s[98:99] nt
	global_load_dwordx4 v[134:137], v252, s[98:99] offset:32 nt
	global_load_dwordx4 v[138:141], v252, s[98:99] offset:64 nt
	global_load_dwordx4 v[142:145], v252, s[98:99] offset:96 nt
	s_mov_b32 s99, 1
.Lqh_skip:
	global_store_dwordx4 v[24:25], v[18:21], off
	v_pk_mul_f32 v[26:27], v[80:81], v[0:1] op_sel_hi:[1,0]
	s_and_b64 vcc, exec, s[70:71]
	v_pk_mul_f32 v[18:19], v[74:75], v[0:1] op_sel_hi:[1,0]
	v_pk_mul_f32 v[20:21], v[76:77], v[0:1] op_sel_hi:[1,0]
	v_cvt_pk_bf16_f32 v18, v18, v19
	v_cvt_pk_bf16_f32 v19, v20, v21
	v_pk_mul_f32 v[20:21], v[78:79], v[0:1] op_sel_hi:[1,0]
	v_readlane_b32 s41, v250, 18
	v_cvt_pk_bf16_f32 v20, v20, v21
	v_cvt_pk_bf16_f32 v21, v26, v27
	s_nop 0
	v_permlane32_swap_b32_e32 v18, v20
	v_permlane32_swap_b32_e32 v19, v21
	global_store_dwordx4 v[24:25], v[18:21], off offset:32
	v_pk_mul_f32 v[26:27], v[56:57], v[0:1] op_sel_hi:[1,0]
	s_nop 0
	v_pk_mul_f32 v[18:19], v[50:51], v[0:1] op_sel_hi:[1,0]
	v_pk_mul_f32 v[20:21], v[52:53], v[0:1] op_sel_hi:[1,0]
	v_cvt_pk_bf16_f32 v18, v18, v19
	v_cvt_pk_bf16_f32 v19, v20, v21
	v_pk_mul_f32 v[20:21], v[54:55], v[0:1] op_sel_hi:[1,0]
	s_nop 0
	v_cvt_pk_bf16_f32 v20, v20, v21
	v_cvt_pk_bf16_f32 v21, v26, v27
	s_nop 0
	v_permlane32_swap_b32_e32 v18, v20
	v_permlane32_swap_b32_e32 v19, v21
	global_store_dwordx4 v[24:25], v[18:21], off offset:64
	v_pk_mul_f32 v[26:27], v[64:65], v[0:1] op_sel_hi:[1,0]
	s_nop 0
	v_pk_mul_f32 v[18:19], v[58:59], v[0:1] op_sel_hi:[1,0]
	v_pk_mul_f32 v[20:21], v[60:61], v[0:1] op_sel_hi:[1,0]
	v_cvt_pk_bf16_f32 v18, v18, v19
	v_cvt_pk_bf16_f32 v19, v20, v21
	v_pk_mul_f32 v[20:21], v[62:63], v[0:1] op_sel_hi:[1,0]
	ds_bpermute_b32 v0, v190, v182
	v_cvt_pk_bf16_f32 v20, v20, v21
	v_cvt_pk_bf16_f32 v21, v26, v27
	s_nop 0
	v_permlane32_swap_b32_e32 v18, v20
	s_waitcnt lgkmcnt(0)
	v_add_f32_e32 v0, v182, v0
	v_add_f32_e32 v0, v28, v0
	v_permlane32_swap_b32_e32 v19, v21
	v_rcp_f32_e32 v0, v0
	global_store_dwordx4 v[24:25], v[18:21], off offset:96
	v_pk_mul_f32 v[2:3], v[2:3], v[0:1] op_sel_hi:[1,0]
	s_nop 0
	v_or_b32_e32 v18, 32, v22
	v_ashrrev_i32_e32 v19, 31, v18
	v_lshlrev_b64 v[18:19], 11, v[18:19]
	v_lshl_add_u64 v[22:23], s[80:81], 0, v[18:19]
	v_pk_mul_f32 v[18:19], v[34:35], v[0:1] op_sel_hi:[1,0]
	v_pk_mul_f32 v[20:21], v[36:37], v[0:1] op_sel_hi:[1,0]
	v_pk_mul_f32 v[4:5], v[4:5], v[0:1] op_sel_hi:[1,0]
	v_cvt_pk_bf16_f32 v18, v18, v19
	v_cvt_pk_bf16_f32 v19, v20, v21
	v_pk_mul_f32 v[20:21], v[38:39], v[0:1] op_sel_hi:[1,0]
	v_pk_mul_f32 v[24:25], v[40:41], v[0:1] op_sel_hi:[1,0]
	v_cvt_pk_bf16_f32 v2, v2, v3
	v_cvt_pk_bf16_f32 v3, v4, v5
	v_pk_mul_f32 v[4:5], v[6:7], v[0:1] op_sel_hi:[1,0]
	v_pk_mul_f32 v[6:7], v[8:9], v[0:1] op_sel_hi:[1,0]
	v_cvt_pk_bf16_f32 v20, v20, v21
	v_cvt_pk_bf16_f32 v21, v24, v25
	v_cvt_pk_bf16_f32 v4, v4, v5
	v_cvt_pk_bf16_f32 v5, v6, v7
	v_permlane32_swap_b32_e32 v18, v20
	v_permlane32_swap_b32_e32 v19, v21
	v_lshl_add_u64 v[22:23], v[22:23], 0, v[176:177]
	v_permlane32_swap_b32_e32 v2, v4
	v_permlane32_swap_b32_e32 v3, v5
	global_store_dwordx4 v[22:23], v[18:21], off
	global_store_dwordx4 v[22:23], v[2:5], off offset:64
	v_pk_mul_f32 v[24:25], v[48:49], v[0:1] op_sel_hi:[1,0]
	v_pk_mul_f32 v[18:19], v[42:43], v[0:1] op_sel_hi:[1,0]
	v_pk_mul_f32 v[20:21], v[44:45], v[0:1] op_sel_hi:[1,0]
	v_pk_mul_f32 v[2:3], v[10:11], v[0:1] op_sel_hi:[1,0]
	v_pk_mul_f32 v[4:5], v[12:13], v[0:1] op_sel_hi:[1,0]
	v_cvt_pk_bf16_f32 v18, v18, v19
	v_cvt_pk_bf16_f32 v19, v20, v21
	v_pk_mul_f32 v[20:21], v[46:47], v[0:1] op_sel_hi:[1,0]
	v_cvt_pk_bf16_f32 v2, v2, v3
	v_cvt_pk_bf16_f32 v3, v4, v5
	v_pk_mul_f32 v[4:5], v[14:15], v[0:1] op_sel_hi:[1,0]
	v_pk_mul_f32 v[6:7], v[16:17], v[0:1] op_sel_hi:[1,0]
	v_cvt_pk_bf16_f32 v20, v20, v21
	v_cvt_pk_bf16_f32 v21, v24, v25
	v_cvt_pk_bf16_f32 v4, v4, v5
	v_cvt_pk_bf16_f32 v5, v6, v7
	v_permlane32_swap_b32_e32 v18, v20
	v_permlane32_swap_b32_e32 v19, v21
	v_permlane32_swap_b32_e32 v2, v4
	v_permlane32_swap_b32_e32 v3, v5
	global_store_dwordx4 v[22:23], v[18:21], off offset:32
	global_store_dwordx4 v[22:23], v[2:5], off offset:96
	s_cbranch_vccz .LBB9_308
